# v65: post-G1 and post-mixers group barriers use per-WG arrival words + per-XCD release word for the XCD stage (no XSUB/XGEN atomics); lq0 WG of each XCD does wbl2 + TOP/TOPGEN
# speedup vs baseline: 1.2659x; 1.0082x over previous
_Z14fwd_megakernel6Params:
	s_mov_b32 s100, 0
	v_writelane_b32 v255, s100, 55
	s_mov_b32 s100, 0
	v_writelane_b32 v255, s100, 56
	s_load_dwordx8 s[68:75], s[0:1], 0xc0
	s_add_u32 s8, s0, 0xe0
	v_and_b32_e32 v160, 0x3ff, v0
	s_addc_u32 s9, s1, 0
	s_mov_b32 s4, 0
	v_cmp_ne_u32_e32 vcc, 0, v160
	v_cmp_eq_u32_e64 s[14:15], 0, v160
	s_and_saveexec_b64 s[10:11], s[14:15]
	s_cbranch_execz .LBB0_2
	s_mov_b32 s5, s4
	s_mov_b32 s6, s4
	s_mov_b32 s7, s4
	v_mov_b64_e32 v[2:3], s[4:5]
	v_mov_b32_e32 v1, 0x13400
	v_mov_b64_e32 v[4:5], s[6:7]
	ds_write_b128 v1, v[2:5]
	v_mov_b32_e32 v1, 0x13410
	ds_write_b128 v1, v[2:5]

.LBB0_415:
	s_getreg_b32 s2, hwreg(HW_REG_XCC_ID, 0, 4)
	s_waitcnt vmcnt(0)
	s_waitcnt lgkmcnt(0)
	s_barrier
	s_and_saveexec_b64 s[0:1], s[14:15]
	s_cbranch_execz .LBB0_467
	v_readlane_b32 s98, v255, 63
	s_nop 0
	s_cmp_lg_u32 s98, 0
	s_cbranch_scc1 .Lhb_full_g1
	s_cmp_lg_u32 s33, 64
	s_cbranch_scc1 .Lhb_full_g1
	buffer_inv sc1
	v_readlane_b32 s98, v255, 56
	v_readlane_b32 s100, v253, 1
	v_readlane_b32 s101, v253, 2
	v_readlane_b32 s99, v253, 0
	v_readlane_b32 vcc_lo, v254, 28
	s_add_i32 s98, s98, 1
	v_writelane_b32 v255, s98, 56
	s_lshl_b32 s99, s99, 14
	s_sub_u32 s100, s100, s99
	s_subb_u32 s101, s101, 0
	s_add_u32 s100, s100, 0xb000
	s_addc_u32 s101, s101, 0
	s_getreg_b32 s99, hwreg(HW_REG_XCC_ID, 0, 4)
	s_and_b32 s99, s99, 15
	s_lshl_b32 s99, s99, 8
	s_lshl_b32 vcc_hi, vcc_lo, 2
	s_add_i32 vcc_hi, vcc_hi, s99
	v_mov_b32_e32 v4, vcc_hi
	v_mov_b32_e32 v5, s98
	global_store_dword v4, v5, s[100:101]
	s_cmp_eq_u32 vcc_lo, 0
	s_cbranch_scc1 .Lhb_lead_g1
	s_lshr_b32 s99, s99, 2
	v_mov_b32_e32 v4, s99
	s_mov_b32 s99, 0

.Lhb_ltop_g1:
	s_mov_b64 exec, 1
	buffer_wbl2 sc1
	v_readlane_b32 vcc_lo, v255, 55
	v_readlane_b32 vcc_hi, v254, 7
	s_nop 1
	s_add_i32 vcc_lo, vcc_lo, 1
	v_mov_b32_e32 v2, vcc_hi
	v_writelane_b32 v255, vcc_lo, 55
	v_mov_b32_e32 v0, vcc_lo
	v_readlane_b32 vcc_hi, v254, 8
	v_mov_b32_e32 v5, 1
	s_nop 1
	v_mov_b32_e32 v3, vcc_hi
	s_waitcnt vmcnt(0)
	global_atomic_add v6, v[2:3], v5, off sc0
	v_readlane_b32 vcc_lo, v254, 9
	v_readlane_b32 vcc_hi, v254, 10
	v_lshlrev_b32_e32 v4, 2, v0
	s_waitcnt vmcnt(0)
	v_mov_b32_e32 v2, vcc_lo
	v_mov_b32_e32 v3, vcc_hi
	v_add_u32_e32 v6, 1, v6
	s_nop 0
	v_cmp_eq_u32_e32 vcc, v6, v4
	s_cbranch_vccz .Lhb_twait_g1
	global_atomic_add v[2:3], v5, off
	s_branch .Lhb_lrel_g1
.Lhb_twait_g1:
	v_mov_b32_e32 v4, 0
.Lhb_tspin_g1:
	s_sleep 1
	global_load_dword v6, v[2:3], off sc1
	v_add_u32_e32 v4, 1, v4
	s_waitcnt vmcnt(0)
	v_cmp_ge_u32_e32 vcc, v6, v0
	s_cbranch_vccnz .Lhb_lrel_g1
	v_cmp_gt_u32_e32 vcc, 0x40000, v4
	s_cbranch_vccnz .Lhb_tspin_g1
.Lhb_lrel_g1:
	s_lshr_b32 s99, s99, 2
	v_mov_b32_e32 v4, s99
	v_mov_b32_e32 v5, s98
	global_store_dword v4, v5, s[100:101] offset:-1024

.LBB0_574:
	s_getreg_b32 s2, hwreg(HW_REG_XCC_ID, 0, 4)
	s_waitcnt vmcnt(0)
	s_barrier
	s_and_saveexec_b64 s[0:1], s[14:15]
	v_readlane_b32 s34, v254, 58
	v_readlane_b32 s35, v254, 59
	s_cbranch_execz .LBB0_626
	v_readlane_b32 s98, v255, 63
	s_nop 0
	s_cmp_lg_u32 s98, 0
	s_cbranch_scc1 .Lhb_full_mix
	s_cmp_lg_u32 s33, 64
	s_cbranch_scc1 .Lhb_full_mix
	v_readlane_b32 s98, v255, 56
	v_readlane_b32 s100, v253, 1
	v_readlane_b32 s101, v253, 2
	v_readlane_b32 s99, v253, 0
	v_readlane_b32 vcc_lo, v254, 28
	s_add_i32 s98, s98, 1
	v_writelane_b32 v255, s98, 56
	s_lshl_b32 s99, s99, 14
	s_sub_u32 s100, s100, s99
	s_subb_u32 s101, s101, 0
	s_add_u32 s100, s100, 0xb000
	s_addc_u32 s101, s101, 0
	s_getreg_b32 s99, hwreg(HW_REG_XCC_ID, 0, 4)
	s_and_b32 s99, s99, 15
	s_lshl_b32 s99, s99, 8
	s_lshl_b32 vcc_hi, vcc_lo, 2
	s_add_i32 vcc_hi, vcc_hi, s99
	v_mov_b32_e32 v4, vcc_hi
	v_mov_b32_e32 v5, s98
	global_store_dword v4, v5, s[100:101]
	s_cmp_eq_u32 vcc_lo, 0
	s_cbranch_scc1 .Lhb_lead_mix
	s_lshr_b32 s99, s99, 2
	v_mov_b32_e32 v4, s99
	s_mov_b32 s99, 0
